# v13: forget-logit items: K loop unrolled with loads two steps ahead, no wait between the two load groups, row-scale/bias loads hoisted
# baseline (speedup 1.0000x reference)
.LBB0_375:
	s_mov_b32 s42, 4
	s_and_b32 s1, s34, 63
	s_ashr_i32 s43, s42, 31
	s_lshl_b32 s33, s1, 7
	s_lshl_b64 s[42:43], s[42:43], 3
	v_readlane_b32 s48, v243, 2
	v_readlane_b32 s49, v243, 3
	s_add_u32 s42, s48, s42
	s_addc_u32 s43, s49, s43
	s_ashr_i32 s39, s35, 6
	s_lshl_b32 s1, s39, 13
	s_or_b32 s33, s33, s1
	s_load_dwordx2 s[42:43], s[42:43], 0x0
	v_add_u32_e32 v0, s33, v23
	v_ashrrev_i32_e32 v1, 31, v0
	v_lshlrev_b64 v[0:1], 11, v[0:1]
	v_lshl_add_u64 v[4:5], v[14:15], 0, v[0:1]
	v_mov_b32_e32 v0, 0
	s_mov_b64 s[50:51], 0
	v_mov_b32_e32 v1, v0
	v_mov_b32_e32 v2, v0
	v_mov_b32_e32 v3, v0
	s_and_b32 s100, s35, 63
	s_lshl_b32 s100, s100, 7
	s_add_i32 s100, s100, s28
	s_add_i32 s100, s100, s1
	v_or_b32_e32 v160, s100, v10
	v_ashrrev_i32_e32 v161, 31, v160
	v_lshl_add_u64 v[160:161], v[160:161], 2, s[66:67]
	global_load_dwordx4 v[160:163], v[160:161], off
	s_waitcnt lgkmcnt(0)
	s_add_u32 s100, s42, s40
	s_addc_u32 s101, s43, s41
	global_load_dword v164, v24, s[100:101]
	v_add_co_u32_e32 v154, vcc, 0x3600000, v12
	s_nop 1
	v_addc_co_u32_e32 v155, vcc, 0, v13, vcc
	global_load_dwordx4 v[16:19], v[4:5], off offset:448
	global_load_dwordx4 v[26:29], v[4:5], off offset:384
	global_load_dwordx4 v[30:33], v[4:5], off offset:320
	global_load_dwordx4 v[34:37], v[4:5], off offset:256
	global_load_dwordx4 v[38:41], v[4:5], off offset:192
	global_load_dwordx4 v[42:45], v[4:5], off offset:128
	global_load_dwordx4 v[46:49], v[4:5], off offset:64
	global_load_dwordx4 v[50:53], v[4:5], off
	global_load_dwordx4 v[54:57], v[154:155], off
	global_load_dwordx4 v[58:61], v[154:155], off offset:64
	global_load_dwordx4 v[62:65], v[154:155], off offset:128
	global_load_dwordx4 v[66:69], v[154:155], off offset:192
	global_load_dwordx4 v[70:73], v[154:155], off offset:256
	global_load_dwordx4 v[74:77], v[154:155], off offset:320
	global_load_dwordx4 v[78:81], v[154:155], off offset:384
	global_load_dwordx4 v[82:85], v[154:155], off offset:448
	global_load_dwordx4 v[118:121], v[4:5], off offset:960
	global_load_dwordx4 v[114:117], v[4:5], off offset:896
	global_load_dwordx4 v[110:113], v[4:5], off offset:832
	global_load_dwordx4 v[106:109], v[4:5], off offset:768
	global_load_dwordx4 v[102:105], v[4:5], off offset:704
	global_load_dwordx4 v[94:97], v[4:5], off offset:640
	global_load_dwordx4 v[90:93], v[4:5], off offset:576
	global_load_dwordx4 v[86:89], v[4:5], off offset:512
	global_load_dwordx4 v[122:125], v[154:155], off offset:512
	global_load_dwordx4 v[126:129], v[154:155], off offset:576
	global_load_dwordx4 v[130:133], v[154:155], off offset:640
	global_load_dwordx4 v[134:137], v[154:155], off offset:704
	global_load_dwordx4 v[138:141], v[154:155], off offset:768
	global_load_dwordx4 v[142:145], v[154:155], off offset:832
	global_load_dwordx4 v[146:149], v[154:155], off offset:896
	global_load_dwordx4 v[150:153], v[154:155], off offset:960
	s_waitcnt vmcnt(16)
	v_mfma_f32_16x16x32_bf16 v[0:3], v[50:53], v[54:57], v[0:3]
	v_mfma_f32_16x16x32_bf16 v[0:3], v[46:49], v[58:61], v[0:3]
	v_mfma_f32_16x16x32_bf16 v[0:3], v[42:45], v[62:65], v[0:3]
	v_mfma_f32_16x16x32_bf16 v[0:3], v[38:41], v[66:69], v[0:3]
	v_mfma_f32_16x16x32_bf16 v[0:3], v[34:37], v[70:73], v[0:3]
	v_mfma_f32_16x16x32_bf16 v[0:3], v[30:33], v[74:77], v[0:3]
	v_mfma_f32_16x16x32_bf16 v[0:3], v[26:29], v[78:81], v[0:3]
	v_mfma_f32_16x16x32_bf16 v[0:3], v[16:19], v[82:85], v[0:3]
	global_load_dwordx4 v[16:19], v[4:5], off offset:1472
	global_load_dwordx4 v[26:29], v[4:5], off offset:1408
	global_load_dwordx4 v[30:33], v[4:5], off offset:1344
	global_load_dwordx4 v[34:37], v[4:5], off offset:1280
	global_load_dwordx4 v[38:41], v[4:5], off offset:1216
	global_load_dwordx4 v[42:45], v[4:5], off offset:1152
	global_load_dwordx4 v[46:49], v[4:5], off offset:1088
	global_load_dwordx4 v[50:53], v[4:5], off offset:1024
	global_load_dwordx4 v[54:57], v[154:155], off offset:1024
	global_load_dwordx4 v[58:61], v[154:155], off offset:1088
	global_load_dwordx4 v[62:65], v[154:155], off offset:1152
	global_load_dwordx4 v[66:69], v[154:155], off offset:1216
	global_load_dwordx4 v[70:73], v[154:155], off offset:1280
	global_load_dwordx4 v[74:77], v[154:155], off offset:1344
	global_load_dwordx4 v[78:81], v[154:155], off offset:1408
	global_load_dwordx4 v[82:85], v[154:155], off offset:1472
	s_waitcnt vmcnt(16)
	v_mfma_f32_16x16x32_bf16 v[0:3], v[86:89], v[122:125], v[0:3]
	v_mfma_f32_16x16x32_bf16 v[0:3], v[90:93], v[126:129], v[0:3]
	v_mfma_f32_16x16x32_bf16 v[0:3], v[94:97], v[130:133], v[0:3]
	v_mfma_f32_16x16x32_bf16 v[0:3], v[102:105], v[134:137], v[0:3]
	v_mfma_f32_16x16x32_bf16 v[0:3], v[106:109], v[138:141], v[0:3]
	v_mfma_f32_16x16x32_bf16 v[0:3], v[110:113], v[142:145], v[0:3]
	v_mfma_f32_16x16x32_bf16 v[0:3], v[114:117], v[146:149], v[0:3]
	v_mfma_f32_16x16x32_bf16 v[0:3], v[118:121], v[150:153], v[0:3]
	global_load_dwordx4 v[118:121], v[4:5], off offset:1984
	global_load_dwordx4 v[114:117], v[4:5], off offset:1920
	global_load_dwordx4 v[110:113], v[4:5], off offset:1856
	global_load_dwordx4 v[106:109], v[4:5], off offset:1792
	global_load_dwordx4 v[102:105], v[4:5], off offset:1728
	global_load_dwordx4 v[94:97], v[4:5], off offset:1664
	global_load_dwordx4 v[90:93], v[4:5], off offset:1600
	global_load_dwordx4 v[86:89], v[4:5], off offset:1536
	global_load_dwordx4 v[122:125], v[154:155], off offset:1536
	global_load_dwordx4 v[126:129], v[154:155], off offset:1600
	global_load_dwordx4 v[130:133], v[154:155], off offset:1664
	global_load_dwordx4 v[134:137], v[154:155], off offset:1728
	global_load_dwordx4 v[138:141], v[154:155], off offset:1792
	global_load_dwordx4 v[142:145], v[154:155], off offset:1856
	global_load_dwordx4 v[146:149], v[154:155], off offset:1920
	global_load_dwordx4 v[150:153], v[154:155], off offset:1984
	s_waitcnt vmcnt(16)
	v_mfma_f32_16x16x32_bf16 v[0:3], v[50:53], v[54:57], v[0:3]
	v_mfma_f32_16x16x32_bf16 v[0:3], v[46:49], v[58:61], v[0:3]
	v_mfma_f32_16x16x32_bf16 v[0:3], v[42:45], v[62:65], v[0:3]
	v_mfma_f32_16x16x32_bf16 v[0:3], v[38:41], v[66:69], v[0:3]
	v_mfma_f32_16x16x32_bf16 v[0:3], v[34:37], v[70:73], v[0:3]
	v_mfma_f32_16x16x32_bf16 v[0:3], v[30:33], v[74:77], v[0:3]
	v_mfma_f32_16x16x32_bf16 v[0:3], v[26:29], v[78:81], v[0:3]
	v_mfma_f32_16x16x32_bf16 v[0:3], v[16:19], v[82:85], v[0:3]
	s_waitcnt vmcnt(0)
	v_mfma_f32_16x16x32_bf16 v[0:3], v[86:89], v[122:125], v[0:3]
	v_mfma_f32_16x16x32_bf16 v[0:3], v[90:93], v[126:129], v[0:3]
	v_mfma_f32_16x16x32_bf16 v[0:3], v[94:97], v[130:133], v[0:3]
	v_mfma_f32_16x16x32_bf16 v[0:3], v[102:105], v[134:137], v[0:3]
	v_mfma_f32_16x16x32_bf16 v[0:3], v[106:109], v[138:141], v[0:3]
	v_mfma_f32_16x16x32_bf16 v[0:3], v[110:113], v[142:145], v[0:3]
	v_mfma_f32_16x16x32_bf16 v[0:3], v[114:117], v[146:149], v[0:3]
	v_mfma_f32_16x16x32_bf16 v[0:3], v[118:121], v[150:153], v[0:3]
	s_mov_b64 s[50:51], 0x800
	s_and_b32 s47, s35, 63
	s_lshl_b32 s48, s47, 7
	s_add_i32 s33, s48, s28
	s_add_i32 s33, s33, s1
	v_or_b32_e32 v4, s33, v10
	v_ashrrev_i32_e32 v5, 31, v4
	v_lshl_add_u64 v[4:5], v[4:5], 2, s[66:67]
	v_mov_b32_e32 v4, v160
	v_mov_b32_e32 v5, v161
	v_mov_b32_e32 v6, v162
	v_mov_b32_e32 v7, v163
	s_waitcnt lgkmcnt(0)
	s_add_u32 s42, s42, s40
	s_addc_u32 s43, s43, s41
	v_mov_b32_e32 v16, v164
	s_mov_b32 s1, 0xbfb8aa3b
	s_mov_b32 s33, 0x3f2aaaab
	s_mov_b32 s42, 0x3f317218
	s_mov_b32 s43, 0x7f800000
	s_mov_b32 s49, 0x33800000
	s_waitcnt vmcnt(1)
	v_fmamk_f32 v4, v4, 0x3a800000, v207
	v_rsq_f32_e32 v4, v4
	v_fmamk_f32 v5, v5, 0x3a800000, v207
	v_rsq_f32_e32 v5, v5
	s_waitcnt vmcnt(0)
	v_fma_f32 v0, v0, v4, v16
	v_mul_f32_e64 v4, |v0|, s1
	v_fma_f32 v1, v1, v5, v16
	v_exp_f32_e32 v17, v4
	v_mul_f32_e64 v5, |v1|, s1
	v_exp_f32_e32 v18, v5
	v_min_f32_e32 v19, 0, v0
	v_add_f32_e32 v26, 1.0, v17
	v_min_f32_e32 v25, 0, v1
	v_frexp_mant_f32_e32 v29, v26
	v_cvt_f64_f32_e32 v[0:1], v26
	v_add_f32_e32 v27, 1.0, v18
	v_add_f32_e32 v28, -1.0, v26
	v_frexp_exp_i32_f64_e32 v0, v[0:1]
	v_cmp_gt_f32_e32 vcc, s33, v29
	v_add_f32_e32 v30, -1.0, v27
	v_frexp_mant_f32_e32 v31, v27
	v_cvt_f64_f32_e32 v[4:5], v27
	v_sub_f32_e32 v32, v28, v26
	v_subbrev_co_u32_e32 v0, vcc, 0, v0, vcc
	v_sub_f32_e32 v28, v17, v28
	v_sub_f32_e32 v1, v30, v27
	v_frexp_exp_i32_f64_e32 v4, v[4:5]
	v_add_f32_e32 v5, 1.0, v32
	v_cmp_gt_f32_e32 vcc, s33, v31
	v_sub_f32_e32 v30, v18, v30
	v_add_f32_e32 v1, 1.0, v1
	v_subbrev_co_u32_e32 v4, vcc, 0, v4, vcc
	v_add_f32_e32 v5, v28, v5
	v_sub_u32_e32 v28, 0, v0
	v_add_f32_e32 v1, v30, v1
	v_sub_u32_e32 v29, 0, v4
	v_ldexp_f32 v26, v26, v28
	v_cvt_f32_i32_e32 v0, v0
	v_ldexp_f32 v5, v5, v28
	v_ldexp_f32 v27, v27, v29
	v_ldexp_f32 v1, v1, v29
	v_add_f32_e32 v28, -1.0, v26
	v_add_f32_e32 v29, 1.0, v26
	v_add_f32_e32 v32, 1.0, v28
	v_add_f32_e32 v33, -1.0, v29
	v_add_f32_e32 v30, -1.0, v27
	v_add_f32_e32 v31, 1.0, v27
	v_sub_f32_e32 v32, v26, v32
	v_sub_f32_e32 v26, v26, v33
	v_add_f32_e32 v34, 1.0, v30
	v_add_f32_e32 v35, -1.0, v31
	v_add_f32_e32 v32, v5, v32
	v_add_f32_e32 v5, v5, v26
	v_mul_f32_e32 v33, 0x3f317218, v0
	v_sub_f32_e32 v34, v27, v34
	v_sub_f32_e32 v27, v27, v35
	v_add_f32_e32 v35, v29, v5
	v_fma_f32 v26, v0, s42, -v33
	v_rcp_f32_e32 v37, v35
	v_fmac_f32_e32 v26, 0xb102e308, v0
	v_sub_f32_e32 v29, v35, v29
	v_add_f32_e32 v38, v33, v26
	v_add_f32_e32 v34, v1, v34
	v_add_f32_e32 v1, v1, v27
	v_add_f32_e32 v27, v28, v32
	v_sub_f32_e32 v5, v5, v29
	v_sub_f32_e32 v29, v38, v33
	v_sub_f32_e32 v28, v27, v28
	v_sub_f32_e32 v26, v26, v29
	v_mul_f32_e32 v29, v27, v37
	v_sub_f32_e32 v28, v32, v28
	v_mul_f32_e32 v32, v35, v29
	v_fma_f32 v33, v29, v35, -v32
	v_fmac_f32_e32 v33, v29, v5
	v_add_f32_e32 v39, v32, v33
	v_sub_f32_e32 v40, v27, v39
	v_sub_f32_e32 v27, v27, v40
	v_sub_f32_e32 v32, v39, v32
	v_sub_f32_e32 v27, v27, v39
	v_sub_f32_e32 v32, v32, v33
	v_add_f32_e32 v27, v28, v27
	v_add_f32_e32 v27, v32, v27
	v_add_f32_e32 v28, v40, v27
	v_mul_f32_e32 v32, v37, v28
	v_sub_f32_e32 v33, v40, v28
	v_mul_f32_e32 v39, v35, v32
	v_add_f32_e32 v27, v27, v33
	v_add_f32_e32 v33, v29, v32
	v_fma_f32 v35, v32, v35, -v39
	v_sub_f32_e32 v29, v33, v29
	v_fmac_f32_e32 v35, v32, v5
	v_sub_f32_e32 v5, v32, v29
	v_add_f32_e32 v29, v39, v35
	v_sub_f32_e32 v32, v29, v39
	v_sub_f32_e32 v39, v28, v29
	v_sub_f32_e32 v28, v28, v39
	v_sub_f32_e32 v28, v28, v29
	v_sub_f32_e32 v32, v32, v35
	v_add_f32_e32 v27, v27, v28
	v_add_f32_e32 v27, v32, v27
	v_add_f32_e32 v27, v39, v27
	v_mul_f32_e32 v27, v37, v27
	v_add_f32_e32 v5, v5, v27
	v_add_f32_e32 v27, v33, v5
	v_mul_f32_e32 v28, v27, v27
	v_sub_f32_e32 v29, v27, v33
	v_fmamk_f32 v33, v28, 0x3e9b6dac, v216
	v_ldexp_f32 v32, v27, 1
	v_mul_f32_e32 v27, v27, v28
	v_fmaak_f32 v28, v28, v33, 0x3f2aaada
	v_mul_f32_e32 v27, v27, v28
	v_add_f32_e32 v28, v32, v27
	v_sub_f32_e32 v5, v5, v29
	v_sub_f32_e32 v29, v28, v32
	v_ldexp_f32 v5, v5, 1
	v_sub_f32_e32 v27, v27, v29
	v_add_f32_e32 v5, v5, v27
	v_add_f32_e32 v27, v28, v5
	v_sub_f32_e32 v28, v27, v28
	v_add_f32_e32 v29, v38, v27
	v_sub_f32_e32 v5, v5, v28
	v_sub_f32_e32 v28, v29, v38
	v_sub_f32_e32 v32, v29, v28
	v_sub_f32_e32 v27, v27, v28
	v_add_f32_e32 v28, v26, v5
	v_sub_f32_e32 v32, v38, v32
	v_sub_f32_e32 v33, v28, v26
	v_add_f32_e32 v27, v27, v32
	v_sub_f32_e32 v32, v28, v33
	v_sub_f32_e32 v5, v5, v33
	v_sub_f32_e32 v26, v26, v32
	v_add_f32_e32 v27, v28, v27
	v_add_f32_e32 v5, v5, v26
	v_add_f32_e32 v26, v29, v27
	v_sub_f32_e32 v28, v26, v29
	v_sub_f32_e32 v27, v27, v28
	v_add_f32_e32 v5, v5, v27
	v_add_f32_e32 v5, v26, v5
	v_cmp_neq_f32_e32 vcc, s43, v17
	v_add_f32_e32 v36, v31, v1
	v_add_f32_e32 v0, v30, v34
	v_cndmask_b32_e32 v5, v222, v5, vcc
	v_cmp_ngt_f32_e32 vcc, -1.0, v17
	v_sub_f32_e32 v26, v36, v31
	v_sub_f32_e32 v1, v1, v26
	v_cndmask_b32_e32 v5, v223, v5, vcc
	v_cmp_neq_f32_e32 vcc, -1.0, v17
	v_sub_f32_e32 v30, v0, v30
	v_cvt_f32_i32_e32 v4, v4
	v_cndmask_b32_e32 v5, v220, v5, vcc
	v_cmp_lt_f32_e64 vcc, |v17|, s49
	s_nop 1
	v_cndmask_b32_e32 v5, v5, v17, vcc
	v_rcp_f32_e32 v17, v36
	v_sub_f32_e32 v5, v19, v5
	v_sub_f32_e32 v19, v34, v30
	v_cmp_neq_f32_e32 vcc, s43, v18
	v_mul_f32_e32 v26, v0, v17
	v_mul_f32_e32 v27, v36, v26
	v_fma_f32 v28, v26, v36, -v27
	v_fmac_f32_e32 v28, v26, v1
	v_add_f32_e32 v29, v27, v28
	v_sub_f32_e32 v30, v0, v29
	v_sub_f32_e32 v0, v0, v30
	v_sub_f32_e32 v27, v29, v27
	v_sub_f32_e32 v0, v0, v29
	v_add_f32_e32 v0, v19, v0
	v_sub_f32_e32 v19, v27, v28
	v_add_f32_e32 v0, v19, v0
	v_add_f32_e32 v19, v30, v0
	v_mul_f32_e32 v27, v17, v19
	v_mul_f32_e32 v28, v36, v27
	v_fma_f32 v29, v27, v36, -v28
	v_fmac_f32_e32 v29, v27, v1
	v_sub_f32_e32 v1, v30, v19
	v_add_f32_e32 v0, v0, v1
	v_add_f32_e32 v1, v28, v29
	v_sub_f32_e32 v30, v19, v1
	v_sub_f32_e32 v19, v19, v30
	v_sub_f32_e32 v28, v1, v28
	v_sub_f32_e32 v1, v19, v1
	v_add_f32_e32 v0, v0, v1
	v_sub_f32_e32 v1, v28, v29
	v_add_f32_e32 v0, v1, v0
	v_add_f32_e32 v0, v30, v0
	v_add_f32_e32 v1, v26, v27
	v_mul_f32_e32 v0, v17, v0
	v_sub_f32_e32 v17, v1, v26
	v_sub_f32_e32 v17, v27, v17
	v_add_f32_e32 v0, v17, v0
	v_mul_f32_e32 v27, 0x3f317218, v4
	v_add_f32_e32 v17, v1, v0
	v_fma_f32 v28, v4, s42, -v27
	v_mul_f32_e32 v19, v17, v17
	v_fmac_f32_e32 v28, 0xb102e308, v4
	v_sub_f32_e32 v1, v17, v1
	v_fmamk_f32 v26, v19, 0x3e9b6dac, v216
	v_sub_f32_e32 v0, v0, v1
	v_add_f32_e32 v1, v27, v28
	v_fmaak_f32 v26, v19, v26, 0x3f2aaada
	v_sub_f32_e32 v4, v1, v27
	v_ldexp_f32 v27, v17, 1
	v_mul_f32_e32 v17, v17, v19
	v_mul_f32_e32 v17, v17, v26
	v_add_f32_e32 v19, v27, v17
	v_sub_f32_e32 v26, v19, v27
	v_ldexp_f32 v0, v0, 1
	v_sub_f32_e32 v17, v17, v26
	v_add_f32_e32 v0, v0, v17
	v_add_f32_e32 v17, v19, v0
	v_sub_f32_e32 v19, v17, v19
	v_sub_f32_e32 v0, v0, v19
	v_add_f32_e32 v19, v1, v17
	v_sub_f32_e32 v26, v19, v1
	v_sub_f32_e32 v27, v19, v26
	v_sub_f32_e32 v4, v28, v4
	v_sub_f32_e32 v1, v1, v27
	v_sub_f32_e32 v17, v17, v26
	v_add_f32_e32 v1, v17, v1
	v_add_f32_e32 v17, v4, v0
	v_sub_f32_e32 v26, v17, v4
	v_sub_f32_e32 v27, v17, v26
	v_sub_f32_e32 v4, v4, v27
	v_sub_f32_e32 v0, v0, v26
	v_add_f32_e32 v1, v17, v1
	v_add_f32_e32 v0, v0, v4
	v_add_f32_e32 v4, v19, v1
	v_sub_f32_e32 v17, v4, v19
	v_sub_f32_e32 v1, v1, v17
	v_add_f32_e32 v0, v0, v1
	v_fmamk_f32 v1, v6, 0x3a800000, v207
	v_add_f32_e32 v0, v4, v0
	v_rsq_f32_e32 v1, v1
	v_cndmask_b32_e32 v0, v222, v0, vcc
	v_cmp_ngt_f32_e32 vcc, -1.0, v18
	v_fma_f32 v2, v2, v1, v16
	s_nop 0
	v_cndmask_b32_e32 v0, v223, v0, vcc
	v_cmp_neq_f32_e32 vcc, -1.0, v18
	s_nop 1
	v_cndmask_b32_e32 v0, v220, v0, vcc
	v_cmp_lt_f32_e64 vcc, |v18|, s49
	s_nop 1
	v_cndmask_b32_e32 v0, v0, v18, vcc
	v_sub_f32_e32 v4, v25, v0
	v_mul_f32_e64 v0, |v2|, s1
	v_exp_f32_e32 v6, v0
	v_add_f32_e32 v0, 0, v5
	v_add_f32_e32 v1, v0, v4
	v_min_f32_e32 v2, 0, v2
	v_add_f32_e32 v17, 1.0, v6
	v_add_f32_e32 v4, -1.0, v17
	v_sub_f32_e32 v5, v4, v17
	v_add_f32_e32 v5, 1.0, v5
	v_sub_f32_e32 v4, v6, v4
	v_add_f32_e32 v18, v4, v5
	v_frexp_mant_f32_e32 v19, v17
	v_cvt_f64_f32_e32 v[4:5], v17
	v_frexp_exp_i32_f64_e32 v4, v[4:5]
	v_cmp_gt_f32_e32 vcc, s33, v19
	s_nop 1
	v_subbrev_co_u32_e32 v4, vcc, 0, v4, vcc
	v_sub_u32_e32 v5, 0, v4
	v_ldexp_f32 v17, v17, v5
	v_ldexp_f32 v5, v18, v5
	v_add_f32_e32 v18, -1.0, v17
	v_add_f32_e32 v26, 1.0, v17
	v_add_f32_e32 v19, 1.0, v18
	v_add_f32_e32 v27, -1.0, v26
	v_sub_f32_e32 v19, v17, v19
	v_sub_f32_e32 v17, v17, v27
	v_add_f32_e32 v19, v5, v19
	v_add_f32_e32 v5, v5, v17
	v_add_f32_e32 v17, v26, v5
	v_rcp_f32_e32 v27, v17
	v_add_f32_e32 v25, v18, v19
	v_sub_f32_e32 v18, v25, v18
	v_sub_f32_e32 v18, v19, v18
	v_sub_f32_e32 v19, v17, v26
	v_sub_f32_e32 v5, v5, v19
	v_mul_f32_e32 v19, v25, v27
	v_mul_f32_e32 v26, v17, v19
	v_fma_f32 v28, v19, v17, -v26
	v_fmac_f32_e32 v28, v19, v5
	v_add_f32_e32 v29, v26, v28
	v_sub_f32_e32 v30, v25, v29
	v_sub_f32_e32 v25, v25, v30
	v_sub_f32_e32 v26, v29, v26
	v_sub_f32_e32 v25, v25, v29
	v_add_f32_e32 v18, v18, v25
	v_sub_f32_e32 v25, v26, v28
	v_add_f32_e32 v18, v25, v18
	v_add_f32_e32 v25, v30, v18
	v_mul_f32_e32 v26, v27, v25
	v_mul_f32_e32 v28, v17, v26
	v_fma_f32 v17, v26, v17, -v28
	v_fmac_f32_e32 v17, v26, v5
	v_sub_f32_e32 v5, v30, v25
	v_add_f32_e32 v5, v18, v5
	v_add_f32_e32 v18, v28, v17
	v_sub_f32_e32 v29, v25, v18
	v_sub_f32_e32 v25, v25, v29
	v_sub_f32_e32 v28, v18, v28
	v_sub_f32_e32 v18, v25, v18
	v_add_f32_e32 v5, v5, v18
	v_sub_f32_e32 v17, v28, v17
	v_cvt_f32_i32_e32 v4, v4
	v_add_f32_e32 v5, v17, v5
	v_add_f32_e32 v17, v19, v26
	v_add_f32_e32 v5, v29, v5
	v_sub_f32_e32 v18, v17, v19
	v_mul_f32_e32 v5, v27, v5
	v_sub_f32_e32 v18, v26, v18
	v_add_f32_e32 v5, v18, v5
	v_mul_f32_e32 v26, 0x3f317218, v4
	v_add_f32_e32 v18, v17, v5
	v_fma_f32 v27, v4, s42, -v26
	v_mul_f32_e32 v19, v18, v18
	v_fmac_f32_e32 v27, 0xb102e308, v4
	v_sub_f32_e32 v4, v18, v17
	v_fmamk_f32 v25, v19, 0x3e9b6dac, v216
	v_sub_f32_e32 v4, v5, v4
	v_add_f32_e32 v5, v26, v27
	v_fmaak_f32 v25, v19, v25, 0x3f2aaada
	v_sub_f32_e32 v17, v5, v26
	v_ldexp_f32 v26, v18, 1
	v_mul_f32_e32 v18, v18, v19
	v_mul_f32_e32 v18, v18, v25
	v_add_f32_e32 v19, v26, v18
	v_sub_f32_e32 v25, v19, v26
	v_ldexp_f32 v4, v4, 1
	v_sub_f32_e32 v18, v18, v25
	v_add_f32_e32 v4, v4, v18
	v_add_f32_e32 v18, v19, v4
	v_sub_f32_e32 v19, v18, v19
	v_sub_f32_e32 v4, v4, v19
	v_add_f32_e32 v19, v5, v18
	v_sub_f32_e32 v25, v19, v5
	v_sub_f32_e32 v26, v19, v25
	v_sub_f32_e32 v17, v27, v17
	v_sub_f32_e32 v5, v5, v26
	v_sub_f32_e32 v18, v18, v25
	v_add_f32_e32 v5, v18, v5
	v_add_f32_e32 v18, v17, v4
	v_sub_f32_e32 v25, v18, v17
	v_sub_f32_e32 v26, v18, v25
	v_sub_f32_e32 v17, v17, v26
	v_sub_f32_e32 v4, v4, v25
	v_add_f32_e32 v5, v18, v5
	v_add_f32_e32 v4, v4, v17
	v_add_f32_e32 v17, v19, v5
	v_sub_f32_e32 v18, v17, v19
	v_sub_f32_e32 v5, v5, v18
	v_add_f32_e32 v4, v4, v5
	v_fmamk_f32 v5, v7, 0x3a800000, v207
	v_rsq_f32_e32 v5, v5
	v_add_f32_e32 v4, v17, v4
	v_cmp_neq_f32_e32 vcc, s43, v6
	v_fmac_f32_e32 v16, v3, v5
	v_mul_f32_e64 v3, |v16|, s1
	v_exp_f32_e32 v5, v3
	v_cndmask_b32_e32 v4, v222, v4, vcc
	v_cmp_ngt_f32_e32 vcc, -1.0, v6
	v_add_f32_e32 v7, 1.0, v5
	s_nop 0
	v_cndmask_b32_e32 v4, v223, v4, vcc
	v_cmp_neq_f32_e32 vcc, -1.0, v6
	v_frexp_mant_f32_e32 v17, v7
	s_nop 0
	v_cndmask_b32_e32 v4, v220, v4, vcc
	v_cmp_lt_f32_e64 vcc, |v6|, s49
	s_nop 1
	v_cndmask_b32_e32 v3, v4, v6, vcc
	v_sub_f32_e32 v4, v2, v3
	v_add_f32_e32 v2, -1.0, v7
	v_sub_f32_e32 v3, v2, v7
	v_add_f32_e32 v3, 1.0, v3
	v_sub_f32_e32 v2, v5, v2
	v_min_f32_e32 v6, 0, v16
	v_add_f32_e32 v16, v2, v3
	v_cvt_f64_f32_e32 v[2:3], v7
	v_frexp_exp_i32_f64_e32 v2, v[2:3]
	v_cmp_gt_f32_e32 vcc, s33, v17
	v_add_f32_e32 v4, v1, v4
	s_nop 0
	v_subbrev_co_u32_e32 v2, vcc, 0, v2, vcc
	v_sub_u32_e32 v3, 0, v2
	v_ldexp_f32 v7, v7, v3
	v_ldexp_f32 v3, v16, v3
	v_add_f32_e32 v16, -1.0, v7
	v_add_f32_e32 v19, 1.0, v7
	v_add_f32_e32 v17, 1.0, v16
	v_add_f32_e32 v25, -1.0, v19
	v_sub_f32_e32 v17, v7, v17
	v_sub_f32_e32 v7, v7, v25
	v_add_f32_e32 v17, v3, v17
	v_add_f32_e32 v3, v3, v7
	v_add_f32_e32 v7, v19, v3
	v_rcp_f32_e32 v25, v7
	v_add_f32_e32 v18, v16, v17
	v_sub_f32_e32 v16, v18, v16
	v_sub_f32_e32 v16, v17, v16
	v_sub_f32_e32 v17, v7, v19
	v_sub_f32_e32 v3, v3, v17
	v_mul_f32_e32 v17, v18, v25
	v_mul_f32_e32 v19, v7, v17
	v_fma_f32 v26, v17, v7, -v19
	v_fmac_f32_e32 v26, v17, v3
	v_add_f32_e32 v27, v19, v26
	v_sub_f32_e32 v28, v18, v27
	v_sub_f32_e32 v18, v18, v28
	v_sub_f32_e32 v19, v27, v19
	v_sub_f32_e32 v18, v18, v27
	v_add_f32_e32 v16, v16, v18
	v_sub_f32_e32 v18, v19, v26
	v_add_f32_e32 v16, v18, v16
	v_add_f32_e32 v18, v28, v16
	v_mul_f32_e32 v19, v25, v18
	v_mul_f32_e32 v26, v7, v19
	v_fma_f32 v7, v19, v7, -v26
	v_fmac_f32_e32 v7, v19, v3
	v_sub_f32_e32 v3, v28, v18
	v_add_f32_e32 v3, v16, v3
	v_add_f32_e32 v16, v26, v7
	v_sub_f32_e32 v27, v18, v16
	v_sub_f32_e32 v18, v18, v27
	v_sub_f32_e32 v26, v16, v26
	v_sub_f32_e32 v16, v18, v16
	v_add_f32_e32 v3, v3, v16
	v_sub_f32_e32 v7, v26, v7
	v_cvt_f32_i32_e32 v2, v2
	v_add_f32_e32 v3, v7, v3
	v_add_f32_e32 v7, v17, v19
	v_add_f32_e32 v3, v27, v3
	v_sub_f32_e32 v16, v7, v17
	v_mul_f32_e32 v3, v25, v3
	v_sub_f32_e32 v16, v19, v16
	v_add_f32_e32 v3, v16, v3
	v_mul_f32_e32 v19, 0x3f317218, v2
	v_add_f32_e32 v16, v7, v3
	v_fma_f32 v25, v2, s42, -v19
	v_mul_f32_e32 v17, v16, v16
	v_fmac_f32_e32 v25, 0xb102e308, v2
	v_sub_f32_e32 v2, v16, v7
	v_fmamk_f32 v18, v17, 0x3e9b6dac, v216
	v_sub_f32_e32 v2, v3, v2
	v_add_f32_e32 v3, v19, v25
	v_fmaak_f32 v18, v17, v18, 0x3f2aaada
	v_sub_f32_e32 v7, v3, v19
	v_ldexp_f32 v19, v16, 1
	v_mul_f32_e32 v16, v16, v17
	v_mul_f32_e32 v16, v16, v18
	v_add_f32_e32 v17, v19, v16
	v_sub_f32_e32 v18, v17, v19
	v_ldexp_f32 v2, v2, 1
	v_sub_f32_e32 v16, v16, v18
	v_add_f32_e32 v2, v2, v16
	v_add_f32_e32 v16, v17, v2
	v_sub_f32_e32 v17, v16, v17
	v_sub_f32_e32 v2, v2, v17
	v_add_f32_e32 v17, v3, v16
	v_sub_f32_e32 v18, v17, v3
	v_sub_f32_e32 v19, v17, v18
	v_sub_f32_e32 v7, v25, v7
	v_sub_f32_e32 v3, v3, v19
	v_sub_f32_e32 v16, v16, v18
	v_add_f32_e32 v3, v16, v3
	v_add_f32_e32 v16, v7, v2
	v_sub_f32_e32 v18, v16, v7
	v_sub_f32_e32 v19, v16, v18
	v_sub_f32_e32 v7, v7, v19
	v_sub_f32_e32 v2, v2, v18
	v_add_f32_e32 v3, v16, v3
	v_add_f32_e32 v2, v2, v7
	v_add_f32_e32 v7, v17, v3
	v_sub_f32_e32 v16, v7, v17
	v_sub_f32_e32 v3, v3, v16
	v_add_f32_e32 v2, v2, v3
	v_add_f32_e32 v2, v7, v2
	v_cmp_neq_f32_e32 vcc, s43, v5
	s_nop 1
	v_cndmask_b32_e32 v2, v222, v2, vcc
	v_cmp_ngt_f32_e32 vcc, -1.0, v5
	s_nop 1
	v_cndmask_b32_e32 v2, v223, v2, vcc
	v_cmp_neq_f32_e32 vcc, -1.0, v5
	s_nop 1
	v_cndmask_b32_e32 v2, v220, v2, vcc
	v_cmp_lt_f32_e64 vcc, |v5|, s49
	s_nop 1
	v_cndmask_b32_e32 v2, v2, v5, vcc
	v_sub_f32_e32 v2, v6, v2
	v_add_f32_e32 v5, v4, v2
	ds_bpermute_b32 v2, v9, v5
	ds_bpermute_b32 v3, v11, v5
	ds_bpermute_b32 v7, v20, v5
	s_waitcnt lgkmcnt(2)
	v_add_f32_e32 v2, 0, v2
	v_cndmask_b32_e64 v2, v2, 0, s[6:7]
	s_waitcnt lgkmcnt(1)
	v_add_f32_e32 v3, v2, v3
	v_cndmask_b32_e64 v6, v2, v3, s[8:9]
	s_waitcnt lgkmcnt(0)
	v_add_f32_e32 v7, v6, v7
	s_and_saveexec_b64 s[42:43], s[10:11]
	v_add_f32_e32 v2, v7, v5
	ds_write_b32 v21, v2
	s_or_b64 exec, exec, s[42:43]
	s_waitcnt lgkmcnt(0)
	s_barrier
	ds_read2_b32 v[2:3], v22 offset1:16
	v_cndmask_b32_e64 v25, v6, v7, s[10:11]
	ds_read2_b32 v[6:7], v22 offset0:32 offset1:48
	s_lshl_b32 s42, s48, 2
	s_mov_b32 s43, s38
	s_waitcnt lgkmcnt(1)
	v_add_f32_e32 v2, 0, v2
	v_cndmask_b32_e64 v16, 0, v2, s[12:13]
	v_add_f32_e32 v17, v3, v16
	v_cndmask_b32_e64 v18, v16, v17, s[14:15]
	ds_read2_b32 v[16:17], v22 offset0:64 offset1:80
	s_waitcnt lgkmcnt(1)
	v_add_f32_e32 v19, v6, v18
	v_cndmask_b32_e64 v18, v18, v19, s[16:17]
	v_add_f32_e32 v19, v7, v18
	v_cndmask_b32_e64 v26, v18, v19, s[18:19]
	ds_read2_b32 v[18:19], v22 offset0:96 offset1:112
	s_waitcnt lgkmcnt(1)
	v_add_f32_e32 v27, v16, v26
	v_cndmask_b32_e64 v26, v26, v27, s[20:21]
	v_add_f32_e32 v27, v17, v26
	v_cndmask_b32_e64 v26, v26, v27, s[22:23]
	s_waitcnt lgkmcnt(0)
	v_add_f32_e32 v27, v18, v26
	v_cndmask_b32_e64 v26, v26, v27, s[24:25]
	v_add_f32_e32 v27, v19, v26
	v_cndmask_b32_e64 v26, v26, v27, s[26:27]
	v_add_f32_e32 v26, v25, v26
	v_pk_add_f32 v[28:29], v[4:5], v[26:27] op_sel_hi:[1,0]
	v_pk_add_f32 v[26:27], v[0:1], v[26:27] op_sel_hi:[1,0]
	v_lshl_or_b32 v0, s39, 4, v8
	v_ashrrev_i32_e32 v1, 31, v0
	v_lshlrev_b64 v[4:5], 15, v[0:1]
	v_lshl_add_u64 v[4:5], s[2:3], 0, v[4:5]
	v_lshl_add_u64 v[4:5], v[4:5], 0, s[42:43]
	v_lshl_add_u64 v[4:5], s[28:29], 2, v[4:5]
	v_lshl_add_u64 v[4:5], v[4:5], 0, v[100:101]
	global_store_dwordx4 v[4:5], v[26:29], off
	s_and_saveexec_b64 s[42:43], s[30:31]
	s_cbranch_execz .LBB0_374
	v_add_f32_e32 v1, v2, v3
	v_add_f32_e32 v1, v1, v6
	v_add_f32_e32 v1, v1, v7
	v_add_f32_e32 v1, v1, v16
	v_add_f32_e32 v1, v1, v17
	v_add_f32_e32 v1, v1, v18
	v_lshl_or_b32 v0, v0, 6, s47
	v_add_f32_e32 v2, v1, v19
	v_ashrrev_i32_e32 v1, 31, v0
	v_lshl_add_u64 v[0:1], v[0:1], 2, s[4:5]
	global_store_dword v[0:1], v2, off
	s_branch .LBB0_374
